# gla_m2 prologue both layers: five BC-table loads issued together and q/k row loads hoisted before the BC wait (was 5-7 serialized load-wait round trips per job)
# speedup vs baseline: 1.0087x; 1.0087x over previous
.LBB0_644:
	s_lshl_b32 s0, s60, 8
	s_add_i32 s12, s0, s54
	s_mul_i32 s0, s12, 0x8200
	v_mov_b32_e32 v171, v180
	s_mul_hi_i32 s1, s12, 0x8200
	s_add_u32 s0, s46, s0
	s_movk_i32 s2, 0x820
	s_addc_u32 s1, s47, s1
	v_lshlrev_b32_e32 v120, 2, v171
	v_lshlrev_b32_e32 v186, 4, v171
	v_ashrrev_i32_e32 v121, 31, v120
	global_load_dwordx4 v[188:191], v186, s[0:1]
	v_add_u32_e32 v172, 0x200, v171
	v_add_u32_e32 v187, 0x2000, v186
	v_lshlrev_b32_e32 v126, 2, v172
	global_load_dwordx4 v[192:195], v187, s[0:1]
	v_add_u32_e32 v173, 0x400, v171
	v_add_u32_e32 v187, 0x4000, v186
	v_lshlrev_b32_e32 v124, 2, v173
	global_load_dwordx4 v[196:199], v187, s[0:1]
	v_add_u32_e32 v174, 0x600, v171
	v_add_u32_e32 v187, 0x6000, v186
	v_lshlrev_b32_e32 v122, 2, v174
	global_load_dwordx4 v[200:203], v187, s[0:1]
	v_cmp_gt_i32_e32 vcc, 32, v171
	v_add_u32_e32 v187, 0x8000, v186
	s_nop 1
	v_cndmask_b32_e32 v187, 0, v187, vcc
	global_load_dwordx4 v[204:207], v187, s[0:1]
	s_ashr_i32 s61, s12, 3
	s_lshl_b32 s0, s61, 6
	s_cmp_lt_i32 s61, 64
	s_cselect_b64 s[20:21], -1, 0
	s_add_i32 s1, s0, 0xfffff000
	s_lshr_b32 s1, s1, 11
	s_ashr_i32 s2, s12, 5
	s_cmp_gt_i32 s61, 63
	v_readlane_b32 s68, v254, 12
	s_cselect_b64 s[24:25], -1, 0
	v_ashrrev_i32_e32 v170, 3, v171
	v_readlane_b32 s74, v254, 18
	v_readlane_b32 s75, v254, 19
	s_and_b64 vcc, s[24:25], exec
	v_add_u32_e32 v116, s0, v170
	v_mov_b64_e32 v[0:1], s[74:75]
	s_cselect_b32 s13, s1, s2
	v_and_b32_e32 v11, 7, v171
	v_mad_i64_i32 v[118:119], s[0:1], v116, s84, v[0:1]
	s_mov_b32 s7, s9
	v_lshl_add_u64 v[0:1], v[118:119], 0, s[6:7]
	v_lshlrev_b32_e32 v176, 4, v11
	v_lshl_add_u64 v[0:1], v[0:1], 0, v[176:177]
	v_add_co_u32_e64 v4, s[0:1], s92, v0
	s_nop 1
	v_addc_co_u32_e64 v5, s[0:1], 0, v1, s[0:1]
	global_load_dwordx4 v[208:211], v[4:5], off
	global_load_dwordx4 v[212:215], v[4:5], off offset:1024
	s_waitcnt vmcnt(2)
	ds_write_b128 v186, v[188:191]
	ds_write_b128 v186, v[192:195] offset:8192
	ds_write_b128 v186, v[196:199] offset:16384
	ds_write_b128 v186, v[200:203] offset:24576
	v_cmp_gt_i32_e64 s[98:99], 32, v171
	s_and_saveexec_b64 s[62:63], s[98:99]
	ds_write_b128 v186, v[204:207] offset:32768
	s_mov_b64 exec, s[62:63]
	s_waitcnt lgkmcnt(0)
	s_barrier
	v_lshlrev_b32_e32 v8, 5, v11
	v_add_u32_e32 v10, 0, v8
	s_movk_i32 s0, 0x104
	v_mad_u64_u32 v[12:13], s[0:1], v170, s0, v[10:11]
	ds_read2_b32 v[14:15], v12 offset1:1
	v_add_u32_e32 v13, 0x607c, v10
	s_mov_b64 s[0:1], 0x1800
	v_mul_u32_u24_e32 v11, 0x900, v11
	s_lshl_b32 s14, s13, 2
	s_mov_b32 s15, s9
	s_mov_b32 s3, s9
	v_readlane_b32 s69, v254, 13
	v_readlane_b32 s70, v254, 14
	v_readlane_b32 s71, v254, 15
	v_readlane_b32 s72, v254, 16
	v_readlane_b32 s73, v254, 17
	v_readlane_b32 s76, v254, 20
	v_readlane_b32 s77, v254, 21
	v_readlane_b32 s78, v254, 22
	v_readlane_b32 s79, v254, 23
	v_readlane_b32 s80, v254, 24
	v_readlane_b32 s81, v254, 25
	v_readlane_b32 s82, v254, 26
	v_readlane_b32 s83, v254, 27
	s_waitcnt vmcnt(1)
	v_lshlrev_b32_e32 v6, 16, v208
	v_and_b32_e32 v20, 0xffff0000, v208
	v_lshlrev_b32_e32 v32, 16, v209
	v_and_b32_e32 v33, 0xffff0000, v209
	v_lshlrev_b32_e32 v40, 16, v210
	v_and_b32_e32 v41, 0xffff0000, v210
	v_lshlrev_b32_e32 v49, 16, v211
	v_and_b32_e32 v16, 0xffff0000, v211
	v_mul_f32_e32 v17, 0x3e000000, v6
	v_mul_f32_e32 v49, 0x3e000000, v49
	s_waitcnt vmcnt(0)
	v_lshlrev_b32_e32 v22, 16, v212
	v_and_b32_e32 v34, 0xffff0000, v212
	v_add_u32_e32 v0, 0x4100, v12
	v_lshlrev_b32_e32 v35, 16, v213
	v_and_b32_e32 v42, 0xffff0000, v213
	v_lshlrev_b32_e32 v37, 16, v214
	v_and_b32_e32 v50, 0xffff0000, v214
	v_lshlrev_b32_e32 v24, 16, v215
	v_and_b32_e32 v9, 0xffff0000, v215
	ds_read2_b32 v[28:29], v0 offset1:1
	ds_read_b128 v[4:7], v10 offset:8320
	ds_read_b128 v[0:3], v10 offset:8336
	ds_read2_b32 v[30:31], v13 offset1:1
	s_waitcnt lgkmcnt(4)
	v_mul_f32_e32 v13, 0x3fb8aa3b, v14
	v_exp_f32_e32 v13, v13
	s_nop 0
	v_mul_f32_e32 v23, v17, v13
	s_waitcnt lgkmcnt(3)
	v_mul_f32_e32 v13, 0x3fb8aa3b, v28
	v_exp_f32_e32 v13, v13
	s_nop 0
	v_mul_f32_e32 v21, v17, v13
	s_waitcnt lgkmcnt(2)
	v_sub_f32_e32 v13, v14, v4
	v_sub_f32_e32 v4, v4, v14
	v_mul_f32_e32 v4, 0x3fb8aa3b, v4
	v_exp_f32_e32 v4, v4
	v_mul_f32_e32 v13, 0x3fb8aa3b, v13
	v_exp_f32_e32 v13, v13
	v_mul_f32_e32 v14, 0x3fb8aa3b, v15
	v_mul_f32_e32 v18, v4, v22
	s_waitcnt lgkmcnt(0)
	v_sub_f32_e32 v4, v28, v30
	v_mul_f32_e32 v4, 0x3fb8aa3b, v4
	v_exp_f32_e32 v4, v4
	v_mul_f32_e32 v19, v17, v13
	v_exp_f32_e32 v14, v14
	v_mul_f32_e32 v17, v17, v4
	v_sub_f32_e32 v4, v30, v28
	v_mul_f32_e32 v4, 0x3fb8aa3b, v4
	v_exp_f32_e32 v4, v4
	s_nop 0
	v_mul_f32_e32 v13, v4, v22
	v_mul_f32_e32 v4, 0x3e000000, v20
	v_mul_f32_e32 v28, v4, v14
	v_mul_f32_e32 v14, 0x3fb8aa3b, v29
	v_exp_f32_e32 v14, v14
	s_nop 0
	v_mul_f32_e32 v27, v4, v14
	v_sub_f32_e32 v14, v15, v5
	v_sub_f32_e32 v5, v5, v15
	v_mul_f32_e32 v5, 0x3fb8aa3b, v5
	v_exp_f32_e32 v5, v5
	v_mul_f32_e32 v14, 0x3fb8aa3b, v14
	v_exp_f32_e32 v14, v14
	v_mul_f32_e32 v25, v5, v34
	v_sub_f32_e32 v5, v29, v31
	v_mul_f32_e32 v5, 0x3fb8aa3b, v5
	v_exp_f32_e32 v5, v5
	v_mul_f32_e32 v26, v4, v14
	ds_read2_b32 v[14:15], v12 offset0:2 offset1:3
	v_mul_f32_e32 v22, v4, v5
	v_sub_f32_e32 v4, v31, v29
	v_mul_f32_e32 v4, 0x3fb8aa3b, v4
	v_exp_f32_e32 v4, v4
	v_add_u32_e32 v29, 0x6084, v10
	ds_read2_b32 v[38:39], v29 offset1:1
	v_mul_f32_e32 v20, v4, v34
	v_add_u32_e32 v4, 0x4108, v12
	ds_read2_b32 v[4:5], v4 offset1:1
	s_waitcnt lgkmcnt(2)
	v_mul_f32_e32 v29, 0x3fb8aa3b, v14
	v_exp_f32_e32 v29, v29
	v_mul_f32_e32 v34, 0x3e000000, v32
	v_mul_f32_e32 v32, v34, v29
	s_waitcnt lgkmcnt(0)
	v_mul_f32_e32 v29, 0x3fb8aa3b, v4
	v_exp_f32_e32 v29, v29
	s_nop 0
	v_mul_f32_e32 v31, v34, v29
	v_sub_f32_e32 v29, v14, v6
	v_sub_f32_e32 v6, v6, v14
	v_mul_f32_e32 v29, 0x3fb8aa3b, v29
	v_mul_f32_e32 v6, 0x3fb8aa3b, v6
	v_exp_f32_e32 v29, v29
	v_exp_f32_e32 v6, v6
	v_mul_f32_e32 v30, v34, v29
	v_mul_f32_e32 v29, v6, v35
	v_sub_f32_e32 v6, v4, v38
	v_sub_f32_e32 v4, v38, v4
	v_mul_f32_e32 v6, 0x3fb8aa3b, v6
	v_mul_f32_e32 v4, 0x3fb8aa3b, v4
	v_exp_f32_e32 v6, v6
	v_exp_f32_e32 v4, v4
	v_mul_f32_e32 v38, 0x3e000000, v40
	v_mul_f32_e32 v14, v34, v6
	v_mul_f32_e32 v6, v4, v35
	v_mul_f32_e32 v4, 0x3e000000, v33
	v_mul_f32_e32 v33, 0x3fb8aa3b, v15
	v_exp_f32_e32 v33, v33
	s_nop 0
	v_mul_f32_e32 v36, v4, v33
	v_mul_f32_e32 v33, 0x3fb8aa3b, v5
	v_exp_f32_e32 v33, v33
	s_nop 0
	v_mul_f32_e32 v35, v4, v33
	v_sub_f32_e32 v33, v15, v7
	v_sub_f32_e32 v7, v7, v15
	v_mul_f32_e32 v33, 0x3fb8aa3b, v33
	v_mul_f32_e32 v7, 0x3fb8aa3b, v7
	v_exp_f32_e32 v33, v33
	v_exp_f32_e32 v7, v7
	v_mul_f32_e32 v34, v4, v33
	v_mul_f32_e32 v33, v7, v42
	v_sub_f32_e32 v7, v5, v39
	v_mul_f32_e32 v7, 0x3fb8aa3b, v7
	v_exp_f32_e32 v7, v7
	s_nop 0
	v_mul_f32_e32 v15, v4, v7
	v_sub_f32_e32 v4, v39, v5
	v_mul_f32_e32 v4, 0x3fb8aa3b, v4
	v_exp_f32_e32 v4, v4
	v_add_u32_e32 v39, 0x4110, v12
	ds_read2_b32 v[52:53], v39 offset1:1
	v_add_u32_e32 v39, 0x608c, v10
	v_mul_f32_e32 v7, v4, v42
	ds_read2_b32 v[4:5], v12 offset0:4 offset1:5
	ds_read2_b32 v[54:55], v39 offset1:1
	v_add_u32_e32 v10, 0x6094, v10
	s_waitcnt lgkmcnt(1)
	v_mul_f32_e32 v39, 0x3fb8aa3b, v4
	v_exp_f32_e32 v39, v39
	s_nop 0
	v_mul_f32_e32 v44, v38, v39
	v_mul_f32_e32 v39, 0x3fb8aa3b, v52
	v_exp_f32_e32 v39, v39
	s_nop 0
	v_mul_f32_e32 v42, v38, v39
	v_sub_f32_e32 v39, v4, v0
	v_sub_f32_e32 v0, v0, v4
	v_mul_f32_e32 v39, 0x3fb8aa3b, v39
	v_mul_f32_e32 v0, 0x3fb8aa3b, v0
	v_exp_f32_e32 v39, v39
	v_exp_f32_e32 v0, v0
	v_mul_f32_e32 v4, 0x3fb8aa3b, v5
	v_exp_f32_e32 v4, v4
	v_mul_f32_e32 v40, v38, v39
	v_mul_f32_e32 v39, v0, v37
	s_waitcnt lgkmcnt(0)
	v_sub_f32_e32 v0, v52, v54
	v_mul_f32_e32 v0, 0x3fb8aa3b, v0
	v_exp_f32_e32 v0, v0
	s_nop 0
	v_mul_f32_e32 v38, v38, v0
	v_sub_f32_e32 v0, v54, v52
	v_mul_f32_e32 v0, 0x3fb8aa3b, v0
	v_exp_f32_e32 v0, v0
	s_nop 0
	v_mul_f32_e32 v37, v0, v37
	v_mul_f32_e32 v0, 0x3e000000, v41
	v_mul_f32_e32 v48, v0, v4
	v_mul_f32_e32 v4, 0x3fb8aa3b, v53
	v_exp_f32_e32 v4, v4
	s_nop 0
	v_mul_f32_e32 v47, v0, v4
	v_sub_f32_e32 v4, v5, v1
	v_sub_f32_e32 v1, v1, v5
	v_mul_f32_e32 v1, 0x3fb8aa3b, v1
	v_exp_f32_e32 v1, v1
	v_mul_f32_e32 v4, 0x3fb8aa3b, v4
	v_exp_f32_e32 v4, v4
	v_mul_f32_e32 v45, v1, v50
	v_sub_f32_e32 v1, v53, v55
	v_mul_f32_e32 v1, 0x3fb8aa3b, v1
	v_exp_f32_e32 v1, v1
	v_mul_f32_e32 v46, v0, v4
	v_add_u32_e32 v4, 0x4118, v12
	ds_read2_b32 v[4:5], v4 offset1:1
	v_mul_f32_e32 v43, v0, v1
	v_sub_f32_e32 v0, v55, v53
	v_mul_f32_e32 v0, 0x3fb8aa3b, v0
	v_exp_f32_e32 v0, v0
	s_nop 0
	v_mul_f32_e32 v41, v0, v50
	ds_read2_b32 v[0:1], v12 offset0:6 offset1:7
	ds_read2_b32 v[50:51], v10 offset1:1
	s_waitcnt lgkmcnt(2)
	v_mul_f32_e32 v12, 0x3fb8aa3b, v4
	v_exp_f32_e32 v12, v12
	s_waitcnt lgkmcnt(1)
	v_mul_f32_e32 v10, 0x3fb8aa3b, v0
	v_sub_f32_e32 v52, v0, v2
	v_sub_f32_e32 v0, v2, v0
	v_mul_f32_e32 v0, 0x3fb8aa3b, v0
	v_exp_f32_e32 v0, v0
	v_mul_f32_e32 v52, 0x3fb8aa3b, v52
	v_exp_f32_e32 v10, v10
	v_exp_f32_e32 v52, v52
	v_mul_f32_e32 v53, v0, v24
	s_waitcnt lgkmcnt(0)
	v_sub_f32_e32 v0, v4, v50
	v_mul_f32_e32 v0, 0x3fb8aa3b, v0
	v_exp_f32_e32 v0, v0
	v_mul_f32_e32 v10, v49, v10
	v_mul_f32_e32 v12, v49, v12
	v_mul_f32_e32 v52, v49, v52
	v_mul_f32_e32 v49, v49, v0
	v_sub_f32_e32 v0, v50, v4
	v_mul_f32_e32 v0, 0x3fb8aa3b, v0
	v_exp_f32_e32 v0, v0
	v_mul_f32_e32 v2, 0x3fb8aa3b, v1
	v_exp_f32_e32 v2, v2
	v_mul_f32_e32 v4, v0, v24
	v_mul_f32_e32 v0, 0x3e000000, v16
	v_mul_f32_e32 v16, v0, v2
	v_mul_f32_e32 v2, 0x3fb8aa3b, v5
	v_exp_f32_e32 v2, v2
	s_nop 0
	v_mul_f32_e32 v24, v0, v2
	v_sub_f32_e32 v2, v1, v3
	v_sub_f32_e32 v1, v3, v1
	v_mul_f32_e32 v1, 0x3fb8aa3b, v1
	v_exp_f32_e32 v1, v1
	v_mul_f32_e32 v2, 0x3fb8aa3b, v2
	v_exp_f32_e32 v2, v2
	v_mul_f32_e32 v54, v1, v9
	v_sub_f32_e32 v1, v5, v51
	v_mul_f32_e32 v1, 0x3fb8aa3b, v1
	v_exp_f32_e32 v1, v1
	v_mul_f32_e32 v50, v0, v2
	v_mul_f32_e32 v55, v0, v1
	v_sub_f32_e32 v0, v51, v5
	v_mul_f32_e32 v0, 0x3fb8aa3b, v0
	v_exp_f32_e32 v0, v0
	s_nop 0
	v_mul_f32_e32 v5, v0, v9
	v_mul_lo_u32 v9, v170, s85
	v_cvt_pk_bf16_f32 v0, v23, v28
	v_cvt_pk_bf16_f32 v1, v32, v36
	v_cvt_pk_bf16_f32 v2, v44, v48
	v_cvt_pk_bf16_f32 v3, v10, v16
	v_add3_u32 v9, 0, v9, v176
	ds_write_b128 v9, v[0:3] offset:54272
	v_cvt_pk_bf16_f32 v0, v21, v27
	v_cvt_pk_bf16_f32 v1, v31, v35
	v_cvt_pk_bf16_f32 v2, v42, v47
	v_cvt_pk_bf16_f32 v3, v12, v24
	ds_write_b128 v9, v[0:3] offset:54400
	v_mul_lo_u32 v9, v170, s87
	v_cvt_pk_bf16_f32 v0, v19, v26
	v_cvt_pk_bf16_f32 v1, v30, v34
	v_cvt_pk_bf16_f32 v2, v40, v46
	v_cvt_pk_bf16_f32 v3, v52, v50
	v_add3_u32 v10, s86, v9, v176
	ds_write_b128 v10, v[0:3]
	v_cvt_pk_bf16_f32 v0, v18, v25
	v_cvt_pk_bf16_f32 v1, v29, v33
	v_cvt_pk_bf16_f32 v2, v39, v45
	v_cvt_pk_bf16_f32 v3, v53, v54
	v_add3_u32 v10, s88, v9, v176
	ds_write_b128 v10, v[0:3]
	v_cvt_pk_bf16_f32 v0, v17, v22
	v_cvt_pk_bf16_f32 v1, v14, v15
	v_cvt_pk_bf16_f32 v2, v38, v43
	v_cvt_pk_bf16_f32 v3, v49, v55
	v_add3_u32 v10, s89, v9, v176
	ds_write_b128 v10, v[0:3]
	v_cvt_pk_bf16_f32 v0, v13, v20
	v_cvt_pk_bf16_f32 v1, v6, v7
	v_cvt_pk_bf16_f32 v2, v37, v41
	v_cvt_pk_bf16_f32 v3, v4, v5
	v_add3_u32 v4, s52, v9, v176
	ds_write_b128 v4, v[0:3]
	v_lshl_add_u64 v[0:1], v[118:119], 0, s[8:9]
	v_mov_b32_e32 v9, v177
	v_lshl_add_u64 v[0:1], v[0:1], 0, v[8:9]
	v_lshl_add_u64 v[4:5], v[0:1], 0, s[0:1]
	v_add_co_u32_e64 v0, s[0:1], s92, v0
	v_lshlrev_b32_e32 v17, 1, v170
	s_nop 0
	v_addc_co_u32_e64 v1, s[0:1], 0, v1, s[0:1]
	global_load_dwordx4 v[0:3], v[0:1], off offset:2048
	s_nop 0
	global_load_dwordx4 v[4:7], v[4:5], off offset:16
	v_add3_u32 v11, s53, v17, v11
	s_lshl_b64 s[0:1], s[14:15], 18
	s_add_u32 s0, s56, s0
	s_addc_u32 s1, s57, s1
	s_or_b32 s2, s14, 1
	s_waitcnt vmcnt(1)
	v_lshlrev_b32_e32 v8, 16, v0
	v_and_b32_e32 v0, 0xffff0000, v0
	v_cvt_pk_bf16_f32 v8, v8, v177
	ds_write_b16 v11, v8
	v_cvt_pk_bf16_f32 v0, v0, v177
	v_lshlrev_b32_e32 v9, 16, v1
	ds_write_b16 v11, v0 offset:144
	v_cvt_pk_bf16_f32 v0, v9, v177
	v_and_b32_e32 v1, 0xffff0000, v1
	ds_write_b16 v11, v0 offset:288
	v_cvt_pk_bf16_f32 v0, v1, v177
	v_lshlrev_b32_e32 v10, 16, v2
	ds_write_b16 v11, v0 offset:432
	v_cvt_pk_bf16_f32 v0, v10, v177
	v_and_b32_e32 v2, 0xffff0000, v2
	ds_write_b16 v11, v0 offset:576
	v_cvt_pk_bf16_f32 v0, v2, v177
	v_lshlrev_b32_e32 v12, 16, v3
	ds_write_b16 v11, v0 offset:720
	v_cvt_pk_bf16_f32 v0, v12, v177
	v_and_b32_e32 v3, 0xffff0000, v3
	ds_write_b16 v11, v0 offset:864
	v_cvt_pk_bf16_f32 v0, v3, v177
	s_waitcnt vmcnt(0)
	v_lshlrev_b32_e32 v13, 16, v4
	ds_write_b16 v11, v0 offset:1008
	v_cvt_pk_bf16_f32 v0, v13, v177
	v_and_b32_e32 v4, 0xffff0000, v4
	ds_write_b16 v11, v0 offset:1152
	v_cvt_pk_bf16_f32 v0, v4, v177
	v_lshlrev_b32_e32 v14, 16, v5
	ds_write_b16 v11, v0 offset:1296
	v_cvt_pk_bf16_f32 v0, v14, v177
	v_and_b32_e32 v5, 0xffff0000, v5
	ds_write_b16 v11, v0 offset:1440
	v_cvt_pk_bf16_f32 v0, v5, v177
	v_lshlrev_b32_e32 v15, 16, v6
	ds_write_b16 v11, v0 offset:1584
	v_cvt_pk_bf16_f32 v0, v15, v177
	v_and_b32_e32 v6, 0xffff0000, v6
	ds_write_b16 v11, v0 offset:1728
	v_cvt_pk_bf16_f32 v0, v6, v177
	v_lshlrev_b32_e32 v16, 16, v7
	ds_write_b16 v11, v0 offset:1872
	v_cvt_pk_bf16_f32 v0, v16, v177
	v_and_b32_e32 v7, 0xffff0000, v7
	ds_write_b16 v11, v0 offset:2016
	v_cvt_pk_bf16_f32 v0, v7, v177
	ds_write_b16 v11, v0 offset:2160
	v_lshlrev_b32_e32 v0, 11, v171
	v_and_b32_e32 v2, 0x7800, v0
	v_mov_b32_e32 v3, v177
	v_lshl_add_u64 v[0:1], s[0:1], 0, v[2:3]
	s_lshl_b64 s[0:1], s[2:3], 18
	s_add_u32 s0, s56, s0
	s_addc_u32 s1, s57, s1
	v_lshl_add_u64 v[2:3], s[0:1], 0, v[2:3]
	s_cbranch_vccz .LBB0_659
	v_ashrrev_i32_e32 v4, 4, v171
	v_ashrrev_i32_e32 v5, 31, v4
	v_lshlrev_b64 v[4:5], 2, v[4:5]
	v_lshl_add_u64 v[6:7], v[0:1], 0, v[4:5]
	v_lshl_add_u64 v[4:5], v[2:3], 0, v[4:5]
	global_load_dword v132, v[6:7], off
	global_load_dword v133, v[6:7], off offset:512
	global_load_dword v134, v[6:7], off offset:1024
	global_load_dword v135, v[6:7], off offset:1536
	global_load_dword v128, v[4:5], off
	global_load_dword v129, v[4:5], off offset:512
	global_load_dword v130, v[4:5], off offset:1024
	global_load_dword v131, v[4:5], off offset:1536
	v_cndmask_b32_e64 v4, 0, 1, s[24:25]
	v_cmp_ne_u32_e64 s[0:1], 1, v4
	s_andn2_b64 vcc, exec, s[24:25]
	s_cbranch_vccz .LBB0_660

.LBB0_1355:
	s_lshl_b32 s0, s29, 8
	s_add_i32 s12, s0, s60
	s_mul_i32 s0, s12, 0x8200
	v_mov_b32_e32 v171, v180
	s_mul_hi_i32 s1, s12, 0x8200
	s_add_u32 s0, s46, s0
	s_movk_i32 s2, 0x820
	s_addc_u32 s1, s47, s1
	v_lshlrev_b32_e32 v120, 2, v171
	v_lshlrev_b32_e32 v186, 4, v171
	v_ashrrev_i32_e32 v121, 31, v120
	global_load_dwordx4 v[188:191], v186, s[0:1]
	v_add_u32_e32 v172, 0x200, v171
	v_add_u32_e32 v187, 0x2000, v186
	v_lshlrev_b32_e32 v126, 2, v172
	global_load_dwordx4 v[192:195], v187, s[0:1]
	v_add_u32_e32 v173, 0x400, v171
	v_add_u32_e32 v187, 0x4000, v186
	v_lshlrev_b32_e32 v124, 2, v173
	global_load_dwordx4 v[196:199], v187, s[0:1]
	v_add_u32_e32 v174, 0x600, v171
	v_add_u32_e32 v187, 0x6000, v186
	v_lshlrev_b32_e32 v122, 2, v174
	global_load_dwordx4 v[200:203], v187, s[0:1]
	v_cmp_gt_i32_e32 vcc, 32, v171
	v_add_u32_e32 v187, 0x8000, v186
	s_nop 1
	v_cndmask_b32_e32 v187, 0, v187, vcc
	global_load_dwordx4 v[204:207], v187, s[0:1]
	s_ashr_i32 s61, s12, 3
	v_readlane_b32 s64, v254, 12
	s_lshl_b32 s0, s61, 6
	v_ashrrev_i32_e32 v170, 3, v171
	v_readlane_b32 s70, v254, 18
	v_readlane_b32 s71, v254, 19
	v_add_u32_e32 v116, s0, v170
	v_and_b32_e32 v19, 7, v171
	v_mov_b64_e32 v[0:1], s[70:71]
	v_mad_i64_i32 v[118:119], s[2:3], v116, s52, v[0:1]
	s_mov_b32 s7, s9
	v_lshl_add_u64 v[0:1], v[118:119], 0, s[6:7]
	v_lshlrev_b32_e32 v176, 4, v19
	v_lshl_add_u64 v[0:1], v[0:1], 0, v[176:177]
	v_add_co_u32_e32 v0, vcc, s34, v0
	s_nop 1
	v_addc_co_u32_e32 v1, vcc, 0, v1, vcc
	global_load_dwordx4 v[4:7], v[0:1], off
	global_load_dwordx4 v[8:11], v[0:1], off offset:1024
	s_waitcnt vmcnt(2)
	ds_write_b128 v186, v[188:191]
	ds_write_b128 v186, v[192:195] offset:8192
	ds_write_b128 v186, v[196:199] offset:16384
	ds_write_b128 v186, v[200:203] offset:24576
	v_cmp_gt_i32_e64 s[98:99], 32, v171
	s_and_saveexec_b64 s[62:63], s[98:99]
	ds_write_b128 v186, v[204:207] offset:32768
	s_mov_b64 exec, s[62:63]
	s_waitcnt lgkmcnt(0)
	s_barrier
	v_lshlrev_b32_e32 v16, 5, v19
	v_add_u32_e32 v18, 0, v16
	ds_read_b128 v[12:15], v18 offset:8320
	ds_read_b128 v[0:3], v18 offset:8336
	s_movk_i32 s1, 0x104
	v_mad_u64_u32 v[20:21], s[2:3], v170, s1, v[18:19]
	v_add_u32_e32 v21, 0x6084, v18
	v_add_u32_e32 v17, 0x607c, v18
	v_add_u32_e32 v30, 0x4100, v20
	v_add_u32_e32 v31, 0x4108, v20
	ds_read2_b32 v[28:29], v20 offset1:1
	ds_read2_b32 v[26:27], v20 offset0:2 offset1:3
	ds_read2_b32 v[24:25], v20 offset0:4 offset1:5
	ds_read2_b32 v[22:23], v20 offset0:6 offset1:7
	ds_read2_b32 v[32:33], v30 offset1:1
	ds_read2_b32 v[34:35], v17 offset1:1
	ds_read2_b32 v[40:41], v31 offset1:1
	ds_read2_b32 v[42:43], v21 offset1:1
	s_waitcnt lgkmcnt(7)
	v_sub_f32_e32 v21, v28, v12
	v_sub_f32_e32 v12, v12, v28
	v_mul_f32_e32 v12, 0x3fb8aa3b, v12
	v_exp_f32_e32 v12, v12
	v_mul_f32_e32 v17, 0x3fb8aa3b, v28
	v_mul_f32_e32 v28, 0x3fb8aa3b, v29
	v_sub_f32_e32 v30, v29, v13
	v_sub_f32_e32 v37, v13, v29
	v_exp_f32_e32 v13, v17
	s_waitcnt lgkmcnt(3)
	v_mul_f32_e32 v17, 0x3fb8aa3b, v32
	s_waitcnt lgkmcnt(2)
	v_sub_f32_e32 v29, v32, v34
	v_sub_f32_e32 v31, v34, v32
	v_exp_f32_e32 v32, v28
	v_mul_f32_e32 v21, 0x3fb8aa3b, v21
	v_mul_f32_e32 v30, 0x3fb8aa3b, v30
	v_mul_f32_e32 v29, 0x3fb8aa3b, v29
	v_mul_f32_e32 v31, 0x3fb8aa3b, v31
	v_exp_f32_e32 v21, v21
	v_exp_f32_e32 v30, v30
	v_exp_f32_e32 v38, v29
	v_exp_f32_e32 v29, v31
	v_mul_f32_e32 v28, 0x3fb8aa3b, v33
	v_exp_f32_e32 v17, v17
	v_exp_f32_e32 v34, v28
	s_mov_b64 s[2:3], 0x1800
	s_cmp_lt_i32 s61, 64
	s_mov_b32 s17, s9
	s_mov_b32 s15, s9
	v_readlane_b32 s65, v254, 13
	v_readlane_b32 s66, v254, 14
	v_readlane_b32 s67, v254, 15
	v_readlane_b32 s68, v254, 16
	v_readlane_b32 s69, v254, 17
	v_readlane_b32 s72, v254, 20
	v_readlane_b32 s73, v254, 21
	v_readlane_b32 s74, v254, 22
	v_readlane_b32 s75, v254, 23
	v_readlane_b32 s76, v254, 24
	v_readlane_b32 s77, v254, 25
	v_readlane_b32 s78, v254, 26
	v_readlane_b32 s79, v254, 27
	s_waitcnt vmcnt(1)
	v_lshlrev_b32_e32 v46, 16, v6
	v_and_b32_e32 v47, 0xffff0000, v6
	s_waitcnt vmcnt(0)
	v_lshlrev_b32_e32 v6, 16, v8
	v_lshlrev_b32_e32 v31, 16, v4
	v_and_b32_e32 v4, 0xffff0000, v4
	v_and_b32_e32 v45, 0xffff0000, v8
	v_mul_f32_e32 v8, v12, v6
	v_sub_f32_e32 v12, v35, v33
	v_lshlrev_b32_e32 v49, 16, v9
	v_and_b32_e32 v50, 0xffff0000, v9
	v_mul_f32_e32 v4, 0x3e000000, v4
	v_mul_f32_e32 v9, 0x3fb8aa3b, v37
	v_mul_f32_e32 v12, 0x3fb8aa3b, v12
	v_lshlrev_b32_e32 v48, 16, v7
	v_and_b32_e32 v36, 0xffff0000, v7
	v_lshlrev_b32_e32 v51, 16, v10
	v_and_b32_e32 v52, 0xffff0000, v10
	v_mul_f32_e32 v7, 0x3e000000, v31
	v_mul_f32_e32 v31, v4, v32
	v_exp_f32_e32 v9, v9
	v_sub_f32_e32 v10, v33, v35
	v_exp_f32_e32 v32, v12
	v_mul_f32_e32 v10, 0x3fb8aa3b, v10
	v_sub_f32_e32 v33, v26, v14
	v_sub_f32_e32 v14, v14, v26
	v_lshlrev_b32_e32 v39, 16, v11
	v_and_b32_e32 v28, 0xffff0000, v11
	v_mul_f32_e32 v11, v7, v21
	v_exp_f32_e32 v10, v10
	v_mul_f32_e32 v21, v4, v30
	v_mul_f32_e32 v30, 0x3fb8aa3b, v26
	v_mul_f32_e32 v14, 0x3fb8aa3b, v14
	v_exp_f32_e32 v30, v30
	v_exp_f32_e32 v14, v14
	v_mul_f32_e32 v12, v9, v45
	v_mul_f32_e32 v9, v32, v45
	s_waitcnt lgkmcnt(1)
	v_mul_f32_e32 v32, 0x3fb8aa3b, v40
	v_mul_f32_e32 v33, 0x3fb8aa3b, v33
	v_lshlrev_b32_e32 v44, 16, v5
	v_exp_f32_e32 v32, v32
	v_exp_f32_e32 v35, v33
	v_mul_f32_e32 v6, v29, v6
	v_mul_f32_e32 v29, v7, v13
	v_mul_f32_e32 v13, v7, v17
	v_mul_f32_e32 v17, v4, v34
	v_mul_f32_e32 v10, v4, v10
	v_mul_f32_e32 v4, 0x3e000000, v44
	v_mul_f32_e32 v34, v4, v30
	v_mul_f32_e32 v30, v14, v49
	s_waitcnt lgkmcnt(0)
	v_sub_f32_e32 v14, v40, v42
	v_sub_f32_e32 v26, v42, v40
	v_mul_f32_e32 v14, 0x3fb8aa3b, v14
	v_mul_f32_e32 v26, 0x3fb8aa3b, v26
	v_mul_f32_e32 v33, v4, v32
	v_mul_f32_e32 v32, v4, v35
	v_exp_f32_e32 v14, v14
	v_exp_f32_e32 v35, v26
	v_mul_f32_e32 v26, 0x3fb8aa3b, v27
	v_and_b32_e32 v5, 0xffff0000, v5
	v_exp_f32_e32 v37, v26
	v_mul_f32_e32 v26, v4, v14
	v_mul_f32_e32 v14, v35, v49
	v_sub_f32_e32 v35, v27, v15
	v_sub_f32_e32 v15, v15, v27
	v_sub_f32_e32 v27, v41, v43
	v_mul_f32_e32 v4, 0x3e000000, v5
	v_mul_f32_e32 v5, 0x3fb8aa3b, v41
	v_mul_f32_e32 v35, 0x3fb8aa3b, v35
	v_mul_f32_e32 v15, 0x3fb8aa3b, v15
	v_mul_f32_e32 v27, 0x3fb8aa3b, v27
	v_exp_f32_e32 v5, v5
	v_exp_f32_e32 v35, v35
	v_exp_f32_e32 v15, v15
	v_exp_f32_e32 v40, v27
	v_mul_f32_e32 v7, v7, v38
	v_mul_f32_e32 v37, v4, v37
	v_mul_f32_e32 v38, v4, v5
	v_mul_f32_e32 v35, v4, v35
	v_mul_f32_e32 v27, v15, v50
	v_mul_f32_e32 v15, v4, v40
	v_sub_f32_e32 v4, v43, v41
	v_mul_f32_e32 v4, 0x3fb8aa3b, v4
	v_exp_f32_e32 v49, v4
	v_add_u32_e32 v4, 0x4110, v20
	ds_read2_b32 v[4:5], v4 offset1:1
	v_add_u32_e32 v40, 0x608c, v18
	v_mul_f32_e32 v41, 0x3fb8aa3b, v24
	v_exp_f32_e32 v53, v41
	v_add_u32_e32 v20, 0x4118, v20
	v_add_u32_e32 v18, 0x6094, v18
	ds_read2_b32 v[40:41], v40 offset1:1
	ds_read2_b32 v[42:43], v20 offset1:1
	ds_read2_b32 v[44:45], v18 offset1:1
	s_waitcnt lgkmcnt(3)
	v_mul_f32_e32 v18, 0x3fb8aa3b, v4
	v_mul_f32_e32 v20, v49, v50
	v_sub_f32_e32 v50, v24, v0
	v_sub_f32_e32 v0, v0, v24
	s_waitcnt lgkmcnt(2)
	v_sub_f32_e32 v24, v4, v40
	v_sub_f32_e32 v4, v40, v4
	v_mul_f32_e32 v50, 0x3fb8aa3b, v50
	v_mul_f32_e32 v0, 0x3fb8aa3b, v0
	v_mul_f32_e32 v4, 0x3fb8aa3b, v4
	v_exp_f32_e32 v50, v50
	v_exp_f32_e32 v0, v0
	v_mul_f32_e32 v24, 0x3fb8aa3b, v24
	v_exp_f32_e32 v4, v4
	v_exp_f32_e32 v18, v18
	v_exp_f32_e32 v24, v24
	v_mul_f32_e32 v46, 0x3e000000, v46
	v_mul_f32_e32 v40, v46, v50
	v_mul_f32_e32 v50, v0, v51
	v_mul_f32_e32 v4, v4, v51
	v_sub_f32_e32 v51, v25, v1
	v_sub_f32_e32 v1, v1, v25
	v_mul_f32_e32 v49, v46, v53
	v_mul_f32_e32 v18, v46, v18
	v_mul_f32_e32 v24, v46, v24
	v_mul_f32_e32 v0, 0x3e000000, v47
	v_mul_f32_e32 v46, 0x3fb8aa3b, v25
	v_mul_f32_e32 v47, 0x3fb8aa3b, v5
	v_mul_f32_e32 v51, 0x3fb8aa3b, v51
	v_mul_f32_e32 v1, 0x3fb8aa3b, v1
	v_exp_f32_e32 v46, v46
	v_exp_f32_e32 v47, v47
	v_exp_f32_e32 v51, v51
	v_exp_f32_e32 v1, v1
	v_mul_f32_e32 v25, v0, v46
	v_mul_f32_e32 v46, v0, v47
	v_mul_f32_e32 v47, v0, v51
	v_mul_f32_e32 v51, v1, v52
	v_sub_f32_e32 v1, v5, v41
	v_mul_f32_e32 v1, 0x3fb8aa3b, v1
	v_exp_f32_e32 v1, v1
	v_sub_f32_e32 v5, v41, v5
	v_mul_f32_e32 v41, 0x3fb8aa3b, v22
	v_mul_f32_e32 v5, 0x3fb8aa3b, v5
	v_mul_f32_e32 v53, v0, v1
	v_mul_f32_e32 v0, 0x3e000000, v48
	v_sub_f32_e32 v48, v22, v2
	v_sub_f32_e32 v2, v2, v22
	s_waitcnt lgkmcnt(0)
	v_sub_f32_e32 v22, v42, v44
	v_mul_f32_e32 v1, 0x3fb8aa3b, v42
	v_mul_f32_e32 v48, 0x3fb8aa3b, v48
	v_mul_f32_e32 v22, 0x3fb8aa3b, v22
	v_exp_f32_e32 v5, v5
	v_exp_f32_e32 v41, v41
	v_exp_f32_e32 v1, v1
	v_exp_f32_e32 v48, v48
	v_exp_f32_e32 v22, v22
	v_mul_f32_e32 v2, 0x3fb8aa3b, v2
	v_exp_f32_e32 v2, v2
	v_mul_f32_e32 v5, v5, v52
	v_mul_f32_e32 v41, v0, v41
	v_mul_f32_e32 v52, v0, v1
	v_mul_f32_e32 v48, v0, v48
	v_mul_f32_e32 v22, v0, v22
	v_sub_f32_e32 v0, v44, v42
	v_mul_f32_e32 v0, 0x3fb8aa3b, v0
	v_mul_f32_e32 v54, v2, v39
	v_exp_f32_e32 v0, v0
	v_mul_f32_e32 v1, 0x3fb8aa3b, v23
	v_mul_f32_e32 v2, 0x3fb8aa3b, v43
	v_exp_f32_e32 v1, v1
	v_exp_f32_e32 v2, v2
	v_mul_f32_e32 v39, v0, v39
	v_mul_f32_e32 v0, 0x3e000000, v36
	v_mul_f32_e32 v36, v0, v1
	v_mul_f32_e32 v42, v0, v2
	v_sub_f32_e32 v1, v23, v3
	v_sub_f32_e32 v2, v3, v23
	v_sub_f32_e32 v3, v43, v45
	v_mul_f32_e32 v1, 0x3fb8aa3b, v1
	v_mul_f32_e32 v2, 0x3fb8aa3b, v2
	v_mul_f32_e32 v3, 0x3fb8aa3b, v3
	v_exp_f32_e32 v1, v1
	v_exp_f32_e32 v2, v2
	v_exp_f32_e32 v3, v3
	v_sub_f32_e32 v23, v45, v43
	v_mul_f32_e32 v43, v0, v1
	v_mul_f32_e32 v44, v2, v28
	v_mul_f32_e32 v45, v0, v3
	v_cvt_pk_bf16_f32 v0, v29, v31
	v_cvt_pk_bf16_f32 v1, v34, v37
	v_cvt_pk_bf16_f32 v2, v49, v25
	v_mul_lo_u32 v25, v170, s53
	v_add3_u32 v25, 0, v25, v176
	v_cvt_pk_bf16_f32 v3, v41, v36
	ds_write_b128 v25, v[0:3] offset:54272
	v_cvt_pk_bf16_f32 v0, v13, v17
	v_cvt_pk_bf16_f32 v1, v33, v38
	v_cvt_pk_bf16_f32 v2, v18, v46
	v_mul_lo_u32 v13, v170, s55
	v_cvt_pk_bf16_f32 v3, v52, v42
	ds_write_b128 v25, v[0:3] offset:54400
	v_cvt_pk_bf16_f32 v0, v11, v21
	v_cvt_pk_bf16_f32 v1, v32, v35
	v_cvt_pk_bf16_f32 v2, v40, v47
	v_add3_u32 v11, s54, v13, v176
	v_cvt_pk_bf16_f32 v3, v48, v43
	ds_write_b128 v11, v[0:3]
	v_cvt_pk_bf16_f32 v0, v8, v12
	v_cvt_pk_bf16_f32 v1, v30, v27
	v_cvt_pk_bf16_f32 v2, v50, v51
	v_add3_u32 v8, s56, v13, v176
	v_mul_f32_e32 v23, 0x3fb8aa3b, v23
	v_cvt_pk_bf16_f32 v3, v54, v44
	ds_write_b128 v8, v[0:3]
	v_cvt_pk_bf16_f32 v0, v7, v10
	v_cvt_pk_bf16_f32 v1, v26, v15
	v_cvt_pk_bf16_f32 v2, v24, v53
	v_add3_u32 v7, s57, v13, v176
	v_exp_f32_e32 v23, v23
	v_cvt_pk_bf16_f32 v3, v22, v45
	ds_write_b128 v7, v[0:3]
	v_cvt_pk_bf16_f32 v0, v6, v9
	v_cvt_pk_bf16_f32 v1, v14, v20
	v_cvt_pk_bf16_f32 v2, v4, v5
	v_lshl_add_u64 v[4:5], v[118:119], 0, s[8:9]
	v_mov_b32_e32 v17, v177
	v_lshl_add_u64 v[8:9], v[4:5], 0, v[16:17]
	v_add_co_u32_e32 v4, vcc, s34, v8
	v_mul_f32_e32 v23, v23, v28
	s_nop 0
	v_addc_co_u32_e32 v5, vcc, 0, v9, vcc
	v_cvt_pk_bf16_f32 v3, v39, v23
	global_load_dwordx4 v[4:7], v[4:5], off offset:2048
	v_lshl_add_u64 v[8:9], v[8:9], 0, s[2:3]
	global_load_dwordx4 v[8:11], v[8:9], off offset:16
	v_add3_u32 v12, s58, v13, v176
	ds_write_b128 v12, v[0:3]
	v_lshlrev_b32_e32 v16, 1, v170
	v_mul_u32_u24_e32 v17, 0x900, v19
	v_add3_u32 v16, s59, v16, v17
	s_cselect_b64 s[2:3], -1, 0
	s_addk_i32 s0, 0xf000
	s_lshr_b32 s0, s0, 11
	s_ashr_i32 s1, s12, 5
	s_cmp_gt_i32 s61, 63
	s_cselect_b64 s[18:19], -1, 0
	s_and_b64 vcc, s[18:19], exec
	s_cselect_b32 s13, s0, s1
	s_lshl_b32 s7, s13, 2
	s_or_b32 s16, s7, 2
	s_lshl_b64 s[0:1], s[16:17], 18
	s_add_u32 s0, s25, s0
	s_addc_u32 s1, s26, s1
	s_or_b32 s14, s7, 3
	s_waitcnt vmcnt(1)
	v_lshlrev_b32_e32 v0, 16, v4
	v_cvt_pk_bf16_f32 v0, v0, v177
	v_and_b32_e32 v1, 0xffff0000, v4
	ds_write_b16 v16, v0
	v_cvt_pk_bf16_f32 v0, v1, v177
	v_lshlrev_b32_e32 v2, 16, v5
	ds_write_b16 v16, v0 offset:144
	v_cvt_pk_bf16_f32 v0, v2, v177
	v_and_b32_e32 v3, 0xffff0000, v5
	ds_write_b16 v16, v0 offset:288
	v_cvt_pk_bf16_f32 v0, v3, v177
	v_lshlrev_b32_e32 v4, 16, v6
	ds_write_b16 v16, v0 offset:432
	v_cvt_pk_bf16_f32 v0, v4, v177
	v_and_b32_e32 v5, 0xffff0000, v6
	ds_write_b16 v16, v0 offset:576
	v_cvt_pk_bf16_f32 v0, v5, v177
	v_lshlrev_b32_e32 v6, 16, v7
	ds_write_b16 v16, v0 offset:720
	v_cvt_pk_bf16_f32 v0, v6, v177
	v_and_b32_e32 v7, 0xffff0000, v7
	ds_write_b16 v16, v0 offset:864
	v_cvt_pk_bf16_f32 v0, v7, v177
	s_waitcnt vmcnt(0)
	v_lshlrev_b32_e32 v12, 16, v8
	ds_write_b16 v16, v0 offset:1008
	v_cvt_pk_bf16_f32 v0, v12, v177
	v_and_b32_e32 v8, 0xffff0000, v8
	ds_write_b16 v16, v0 offset:1152
	v_cvt_pk_bf16_f32 v0, v8, v177
	v_lshlrev_b32_e32 v13, 16, v9
	ds_write_b16 v16, v0 offset:1296
	v_cvt_pk_bf16_f32 v0, v13, v177
	v_and_b32_e32 v9, 0xffff0000, v9
	ds_write_b16 v16, v0 offset:1440
	v_cvt_pk_bf16_f32 v0, v9, v177
	v_lshlrev_b32_e32 v14, 16, v10
	ds_write_b16 v16, v0 offset:1584
	v_cvt_pk_bf16_f32 v0, v14, v177
	v_and_b32_e32 v10, 0xffff0000, v10
	ds_write_b16 v16, v0 offset:1728
	v_cvt_pk_bf16_f32 v0, v10, v177
	v_lshlrev_b32_e32 v15, 16, v11
	ds_write_b16 v16, v0 offset:1872
	v_cvt_pk_bf16_f32 v0, v15, v177
	v_and_b32_e32 v11, 0xffff0000, v11
	ds_write_b16 v16, v0 offset:2016
	v_cvt_pk_bf16_f32 v0, v11, v177
	ds_write_b16 v16, v0 offset:2160
	v_lshlrev_b32_e32 v0, 11, v171
	v_and_b32_e32 v2, 0x7800, v0
	v_mov_b32_e32 v3, v177
	v_lshl_add_u64 v[0:1], s[0:1], 0, v[2:3]
	s_lshl_b64 s[0:1], s[14:15], 18
	s_add_u32 s0, s25, s0
	s_addc_u32 s1, s26, s1
	v_lshl_add_u64 v[2:3], s[0:1], 0, v[2:3]
	s_cbranch_vccz .LBB0_1370
	v_ashrrev_i32_e32 v4, 4, v171
	v_ashrrev_i32_e32 v5, 31, v4
	v_lshlrev_b64 v[4:5], 2, v[4:5]
	v_lshl_add_u64 v[6:7], v[0:1], 0, v[4:5]
	v_lshl_add_u64 v[4:5], v[2:3], 0, v[4:5]
	global_load_dword v132, v[6:7], off
	global_load_dword v133, v[6:7], off offset:512
	global_load_dword v134, v[6:7], off offset:1024
	global_load_dword v135, v[6:7], off offset:1536
	global_load_dword v128, v[4:5], off
	global_load_dword v129, v[4:5], off offset:512
	global_load_dword v130, v[4:5], off offset:1024
	global_load_dword v131, v[4:5], off offset:1536
	v_cndmask_b32_e64 v4, 0, 1, s[18:19]
	v_cmp_ne_u32_e64 s[0:1], 1, v4
	s_andn2_b64 vcc, exec, s[18:19]
	s_cbranch_vccz .LBB0_1371

	.amdhsa_kernel _Z11mega_kernel6Params
		.amdhsa_group_segment_fixed_size 0
		.amdhsa_private_segment_fixed_size 0
		.amdhsa_kernarg_size 672
		.amdhsa_user_sgpr_count 2
		.amdhsa_user_sgpr_dispatch_ptr 0
		.amdhsa_user_sgpr_queue_ptr 0
		.amdhsa_user_sgpr_kernarg_segment_ptr 1
		.amdhsa_user_sgpr_dispatch_id 0
		.amdhsa_user_sgpr_kernarg_preload_length 0
		.amdhsa_user_sgpr_kernarg_preload_offset 0
		.amdhsa_user_sgpr_private_segment_size 0
		.amdhsa_uses_dynamic_stack 0
		.amdhsa_enable_private_segment 0
		.amdhsa_system_sgpr_workgroup_id_x 1
		.amdhsa_system_sgpr_workgroup_id_y 0
		.amdhsa_system_sgpr_workgroup_id_z 0
		.amdhsa_system_sgpr_workgroup_info 0
		.amdhsa_system_vgpr_workitem_id 2
		.amdhsa_next_free_vgpr 255
		.amdhsa_next_free_sgpr 100
		.amdhsa_accum_offset 256
		.amdhsa_reserve_vcc 1
		.amdhsa_float_round_mode_32 0
		.amdhsa_float_round_mode_16_64 0
		.amdhsa_float_denorm_mode_32 3
		.amdhsa_float_denorm_mode_16_64 3
		.amdhsa_dx10_clamp 1
		.amdhsa_ieee_mode 1
		.amdhsa_fp16_overflow 0
		.amdhsa_tg_split 0
		.amdhsa_exception_fp_ieee_invalid_op 0
		.amdhsa_exception_fp_denorm_src 0
		.amdhsa_exception_fp_ieee_div_zero 0
		.amdhsa_exception_fp_ieee_overflow 0
		.amdhsa_exception_fp_ieee_underflow 0
		.amdhsa_exception_fp_ieee_inexact 0
		.amdhsa_exception_int_div_zero 0
	.end_amdhsa_kernel

.Lfunc_end0:
	.size	_Z11mega_kernel6Params, .Lfunc_end0-_Z11mega_kernel6Params
	.set _Z11mega_kernel6Params.num_vgpr, 255
	.set _Z11mega_kernel6Params.num_agpr, 0
	.set _Z11mega_kernel6Params.numbered_sgpr, 100
	.set _Z11mega_kernel6Params.num_named_barrier, 0
	.set _Z11mega_kernel6Params.private_seg_size, 0
	.set _Z11mega_kernel6Params.uses_vcc, 1
	.set _Z11mega_kernel6Params.uses_flat_scratch, 0
	.set _Z11mega_kernel6Params.has_dyn_sized_stack, 0
	.set _Z11mega_kernel6Params.has_recursion, 0
	.set _Z11mega_kernel6Params.has_indirect_call, 0

amdhsa.kernels:
  - .agpr_count:     0
    .args:
      - .offset:         0
        .size:           416
        .value_kind:     by_value
      - .offset:         416
        .size:           4
        .value_kind:     hidden_block_count_x
      - .offset:         420
        .size:           4
        .value_kind:     hidden_block_count_y
      - .offset:         424
        .size:           4
        .value_kind:     hidden_block_count_z
      - .offset:         428
        .size:           2
        .value_kind:     hidden_group_size_x
      - .offset:         430
        .size:           2
        .value_kind:     hidden_group_size_y
      - .offset:         432
        .size:           2
        .value_kind:     hidden_group_size_z
      - .offset:         434
        .size:           2
        .value_kind:     hidden_remainder_x
      - .offset:         436
        .size:           2
        .value_kind:     hidden_remainder_y
      - .offset:         438
        .size:           2
        .value_kind:     hidden_remainder_z
      - .offset:         456
        .size:           8
        .value_kind:     hidden_global_offset_x
      - .offset:         464
        .size:           8
        .value_kind:     hidden_global_offset_y
      - .offset:         472
        .size:           8
        .value_kind:     hidden_global_offset_z
      - .offset:         480
        .size:           2
        .value_kind:     hidden_grid_dims
      - .offset:         504
        .size:           8
        .value_kind:     hidden_multigrid_sync_arg
      - .offset:         536
        .size:           4
        .value_kind:     hidden_dynamic_lds_size
    .group_segment_fixed_size: 0
    .kernarg_segment_align: 8
    .kernarg_segment_size: 672
    .language:       OpenCL C
    .language_version:
      - 2
      - 0
    .max_flat_workgroup_size: 512
    .name:           _Z11mega_kernel6Params
    .private_segment_fixed_size: 0
    .sgpr_count:     106
    .sgpr_spill_count: 102
    .symbol:         _Z11mega_kernel6Params.kd
    .uniform_work_group_size: 1
    .uses_dynamic_stack: false
    .vgpr_count:     255
    .vgpr_spill_count: 0
    .wavefront_size: 64
